# GEMM K-loop headers aligned to 64 bytes (s_nop padding)
# speedup vs baseline: 1.0028x; 1.0015x over previous
.LBB0_503:
	s_ashr_i32 s13, s12, 31
	s_lshl_b64 s[14:15], s[12:13], 20
	v_readlane_b32 s16, v234, 22
	v_readlane_b32 s17, v234, 23
	s_add_u32 s14, s16, s14
	s_addc_u32 s15, s17, s15
	s_and_b64 s[16:17], s[0:1], exec
	s_cselect_b32 s13, s15, s21
	s_cselect_b32 s42, s14, s20
	s_ashr_i32 s3, s2, 31
	s_lshl_b64 s[16:17], s[2:3], 20
	s_add_u32 s16, s10, s16
	s_addc_u32 s17, s11, s17
	s_and_b64 s[24:25], s[0:1], exec
	s_cselect_b32 s3, s17, s23
	s_cselect_b32 s43, s16, s22
	s_add_u32 s20, s20, 0x80080
	s_addc_u32 s21, s21, 0
	s_add_u32 s44, s22, 0x100
	v_mov_b32_e32 v0, 0
	s_addc_u32 s45, s23, 0
	s_mov_b32 s46, -2
	v_mov_b32_e32 v1, v0
	v_mov_b32_e32 v2, v0
	v_mov_b32_e32 v3, v0
	v_mov_b32_e32 v8, v0
	v_mov_b32_e32 v9, v0
	v_mov_b32_e32 v10, v0
	v_mov_b32_e32 v11, v0
	v_mov_b32_e32 v16, v0
	v_mov_b32_e32 v17, v0
	v_mov_b32_e32 v18, v0
	v_mov_b32_e32 v19, v0
	v_mov_b32_e32 v24, v0
	v_mov_b32_e32 v25, v0
	v_mov_b32_e32 v26, v0
	v_mov_b32_e32 v27, v0
	v_mov_b32_e32 v32, v0
	v_mov_b32_e32 v33, v0
	v_mov_b32_e32 v34, v0
	v_mov_b32_e32 v35, v0
	v_mov_b32_e32 v40, v0
	v_mov_b32_e32 v41, v0
	v_mov_b32_e32 v42, v0
	v_mov_b32_e32 v43, v0
	v_mov_b32_e32 v48, v0
	v_mov_b32_e32 v49, v0
	v_mov_b32_e32 v50, v0
	v_mov_b32_e32 v51, v0
	v_mov_b32_e32 v56, v0
	v_mov_b32_e32 v57, v0
	v_mov_b32_e32 v58, v0
	v_mov_b32_e32 v59, v0
	v_mov_b32_e32 v4, v0
	v_mov_b32_e32 v5, v0
	v_mov_b32_e32 v6, v0
	v_mov_b32_e32 v7, v0
	v_mov_b32_e32 v12, v0
	v_mov_b32_e32 v13, v0
	v_mov_b32_e32 v14, v0
	v_mov_b32_e32 v15, v0
	v_mov_b32_e32 v20, v0
	v_mov_b32_e32 v21, v0
	v_mov_b32_e32 v22, v0
	v_mov_b32_e32 v23, v0
	v_mov_b32_e32 v28, v0
	v_mov_b32_e32 v29, v0
	v_mov_b32_e32 v30, v0
	v_mov_b32_e32 v31, v0
	v_mov_b32_e32 v36, v0
	v_mov_b32_e32 v37, v0
	v_mov_b32_e32 v38, v0
	v_mov_b32_e32 v39, v0
	v_mov_b32_e32 v44, v0
	v_mov_b32_e32 v45, v0
	v_mov_b32_e32 v46, v0
	v_mov_b32_e32 v47, v0
	v_mov_b32_e32 v52, v0
	v_mov_b32_e32 v53, v0
	v_mov_b32_e32 v54, v0
	v_mov_b32_e32 v55, v0
	v_mov_b32_e32 v60, v0
	v_mov_b32_e32 v61, v0
	v_mov_b32_e32 v62, v0
	v_mov_b32_e32 v63, v0
	v_mov_b32_e32 v64, v0
	v_mov_b32_e32 v65, v0
	v_mov_b32_e32 v66, v0
	v_mov_b32_e32 v67, v0
	v_mov_b32_e32 v72, v0
	v_mov_b32_e32 v73, v0
	v_mov_b32_e32 v74, v0
	v_mov_b32_e32 v75, v0
	v_mov_b32_e32 v80, v0
	v_mov_b32_e32 v81, v0
	v_mov_b32_e32 v82, v0
	v_mov_b32_e32 v83, v0
	v_mov_b32_e32 v88, v0
	v_mov_b32_e32 v89, v0
	v_mov_b32_e32 v90, v0
	v_mov_b32_e32 v91, v0
	v_mov_b32_e32 v96, v0
	v_mov_b32_e32 v97, v0
	v_mov_b32_e32 v98, v0
	v_mov_b32_e32 v99, v0
	v_mov_b32_e32 v104, v0
	v_mov_b32_e32 v105, v0
	v_mov_b32_e32 v106, v0
	v_mov_b32_e32 v107, v0
	v_mov_b32_e32 v112, v0
	v_mov_b32_e32 v113, v0
	v_mov_b32_e32 v114, v0
	v_mov_b32_e32 v115, v0
	v_mov_b32_e32 v120, v0
	v_mov_b32_e32 v121, v0
	v_mov_b32_e32 v122, v0
	v_mov_b32_e32 v123, v0
	v_mov_b32_e32 v68, v0
	v_mov_b32_e32 v69, v0
	v_mov_b32_e32 v70, v0
	v_mov_b32_e32 v71, v0
	v_mov_b32_e32 v76, v0
	v_mov_b32_e32 v77, v0
	v_mov_b32_e32 v78, v0
	v_mov_b32_e32 v79, v0
	v_mov_b32_e32 v84, v0
	v_mov_b32_e32 v85, v0
	v_mov_b32_e32 v86, v0
	v_mov_b32_e32 v87, v0
	v_mov_b32_e32 v92, v0
	v_mov_b32_e32 v93, v0
	v_mov_b32_e32 v94, v0
	v_mov_b32_e32 v95, v0
	v_mov_b32_e32 v100, v0
	v_mov_b32_e32 v101, v0
	v_mov_b32_e32 v102, v0
	v_mov_b32_e32 v103, v0
	v_mov_b32_e32 v108, v0
	v_mov_b32_e32 v109, v0
	v_mov_b32_e32 v110, v0
	v_mov_b32_e32 v111, v0
	v_mov_b32_e32 v116, v0
	v_mov_b32_e32 v117, v0
	v_mov_b32_e32 v118, v0
	v_mov_b32_e32 v119, v0
	v_mov_b32_e32 v124, v0
	v_mov_b32_e32 v125, v0
	v_mov_b32_e32 v126, v0
	v_mov_b32_e32 v127, v0
	.p2alignl 6, 3212836864

.LBB0_1012:
	s_add_u32 s46, s22, 0x100
	v_mov_b32_e32 v0, 0
	s_addc_u32 s47, s23, 0
	s_mov_b32 s48, -2
	s_waitcnt lgkmcnt(0)
	v_mov_b32_e32 v1, v0
	v_mov_b32_e32 v2, v0
	v_mov_b32_e32 v3, v0
	v_mov_b32_e32 v4, v0
	v_mov_b32_e32 v5, v0
	v_mov_b32_e32 v6, v0
	v_mov_b32_e32 v7, v0
	v_mov_b32_e32 v16, v0
	v_mov_b32_e32 v17, v0
	v_mov_b32_e32 v18, v0
	v_mov_b32_e32 v19, v0
	v_mov_b32_e32 v20, v0
	v_mov_b32_e32 v21, v0
	v_mov_b32_e32 v22, v0
	v_mov_b32_e32 v23, v0
	v_mov_b32_e32 v32, v0
	v_mov_b32_e32 v33, v0
	v_mov_b32_e32 v34, v0
	v_mov_b32_e32 v35, v0
	v_mov_b32_e32 v36, v0
	v_mov_b32_e32 v37, v0
	v_mov_b32_e32 v38, v0
	v_mov_b32_e32 v39, v0
	v_mov_b32_e32 v48, v0
	v_mov_b32_e32 v49, v0
	v_mov_b32_e32 v50, v0
	v_mov_b32_e32 v51, v0
	v_mov_b32_e32 v52, v0
	v_mov_b32_e32 v53, v0
	v_mov_b32_e32 v54, v0
	v_mov_b32_e32 v55, v0
	v_mov_b32_e32 v8, v0
	v_mov_b32_e32 v9, v0
	v_mov_b32_e32 v10, v0
	v_mov_b32_e32 v11, v0
	v_mov_b32_e32 v12, v0
	v_mov_b32_e32 v13, v0
	v_mov_b32_e32 v14, v0
	v_mov_b32_e32 v15, v0
	v_mov_b32_e32 v24, v0
	v_mov_b32_e32 v25, v0
	v_mov_b32_e32 v26, v0
	v_mov_b32_e32 v27, v0
	v_mov_b32_e32 v28, v0
	v_mov_b32_e32 v29, v0
	v_mov_b32_e32 v30, v0
	v_mov_b32_e32 v31, v0
	v_mov_b32_e32 v40, v0
	v_mov_b32_e32 v41, v0
	v_mov_b32_e32 v42, v0
	v_mov_b32_e32 v43, v0
	v_mov_b32_e32 v44, v0
	v_mov_b32_e32 v45, v0
	v_mov_b32_e32 v46, v0
	v_mov_b32_e32 v47, v0
	v_mov_b32_e32 v56, v0
	v_mov_b32_e32 v57, v0
	v_mov_b32_e32 v58, v0
	v_mov_b32_e32 v59, v0
	v_mov_b32_e32 v60, v0
	v_mov_b32_e32 v61, v0
	v_mov_b32_e32 v62, v0
	v_mov_b32_e32 v63, v0
	v_mov_b32_e32 v64, v0
	v_mov_b32_e32 v65, v0
	v_mov_b32_e32 v66, v0
	v_mov_b32_e32 v67, v0
	v_mov_b32_e32 v68, v0
	v_mov_b32_e32 v69, v0
	v_mov_b32_e32 v70, v0
	v_mov_b32_e32 v71, v0
	v_mov_b32_e32 v80, v0
	v_mov_b32_e32 v81, v0
	v_mov_b32_e32 v82, v0
	v_mov_b32_e32 v83, v0
	v_mov_b32_e32 v84, v0
	v_mov_b32_e32 v85, v0
	v_mov_b32_e32 v86, v0
	v_mov_b32_e32 v87, v0
	v_mov_b32_e32 v96, v0
	v_mov_b32_e32 v97, v0
	v_mov_b32_e32 v98, v0
	v_mov_b32_e32 v99, v0
	v_mov_b32_e32 v100, v0
	v_mov_b32_e32 v101, v0
	v_mov_b32_e32 v102, v0
	v_mov_b32_e32 v103, v0
	v_mov_b32_e32 v112, v0
	v_mov_b32_e32 v113, v0
	v_mov_b32_e32 v114, v0
	v_mov_b32_e32 v115, v0
	v_mov_b32_e32 v116, v0
	v_mov_b32_e32 v117, v0
	v_mov_b32_e32 v118, v0
	v_mov_b32_e32 v119, v0
	v_mov_b32_e32 v72, v0
	v_mov_b32_e32 v73, v0
	v_mov_b32_e32 v74, v0
	v_mov_b32_e32 v75, v0
	v_mov_b32_e32 v76, v0
	v_mov_b32_e32 v77, v0
	v_mov_b32_e32 v78, v0
	v_mov_b32_e32 v79, v0
	v_mov_b32_e32 v88, v0
	v_mov_b32_e32 v89, v0
	v_mov_b32_e32 v90, v0
	v_mov_b32_e32 v91, v0
	v_mov_b32_e32 v92, v0
	v_mov_b32_e32 v93, v0
	v_mov_b32_e32 v94, v0
	v_mov_b32_e32 v95, v0
	v_mov_b32_e32 v104, v0
	v_mov_b32_e32 v105, v0
	v_mov_b32_e32 v106, v0
	v_mov_b32_e32 v107, v0
	v_mov_b32_e32 v108, v0
	v_mov_b32_e32 v109, v0
	v_mov_b32_e32 v110, v0
	v_mov_b32_e32 v111, v0
	v_mov_b32_e32 v120, v0
	v_mov_b32_e32 v121, v0
	v_mov_b32_e32 v122, v0
	v_mov_b32_e32 v123, v0
	v_mov_b32_e32 v124, v0
	v_mov_b32_e32 v125, v0
	v_mov_b32_e32 v126, v0
	v_mov_b32_e32 v127, v0
	.p2alignl 6, 3212836864

.LBB0_1113:
	s_ashr_i32 s29, s28, 31
	s_lshl_b64 s[30:31], s[28:29], 20
	v_readlane_b32 s34, v234, 22
	v_readlane_b32 s35, v234, 23
	s_add_u32 s30, s34, s30
	s_addc_u32 s31, s35, s31
	s_and_b64 s[34:35], s[4:5], exec
	s_cselect_b32 s1, s31, s9
	s_cselect_b32 s7, s30, s8
	s_ashr_i32 s27, s26, 31
	s_lshl_b64 s[34:35], s[26:27], 20
	s_add_u32 s34, s18, s34
	s_addc_u32 s35, s19, s35
	s_and_b64 s[38:39], s[4:5], exec
	s_cselect_b32 s27, s35, s37
	s_cselect_b32 s29, s34, s36
	s_add_u32 s8, s8, 0x80080
	s_addc_u32 s9, s9, 0
	s_add_u32 s56, s36, 0x100
	v_mov_b32_e32 v0, 0
	s_addc_u32 s57, s37, 0
	s_mov_b32 s58, -2
	v_mov_b32_e32 v1, v0
	v_mov_b32_e32 v2, v0
	v_mov_b32_e32 v3, v0
	v_mov_b32_e32 v4, v0
	v_mov_b32_e32 v5, v0
	v_mov_b32_e32 v6, v0
	v_mov_b32_e32 v7, v0
	v_mov_b32_e32 v16, v0
	v_mov_b32_e32 v17, v0
	v_mov_b32_e32 v18, v0
	v_mov_b32_e32 v19, v0
	v_mov_b32_e32 v20, v0
	v_mov_b32_e32 v21, v0
	v_mov_b32_e32 v22, v0
	v_mov_b32_e32 v23, v0
	v_mov_b32_e32 v32, v0
	v_mov_b32_e32 v33, v0
	v_mov_b32_e32 v34, v0
	v_mov_b32_e32 v35, v0
	v_mov_b32_e32 v36, v0
	v_mov_b32_e32 v37, v0
	v_mov_b32_e32 v38, v0
	v_mov_b32_e32 v39, v0
	v_mov_b32_e32 v48, v0
	v_mov_b32_e32 v49, v0
	v_mov_b32_e32 v50, v0
	v_mov_b32_e32 v51, v0
	v_mov_b32_e32 v52, v0
	v_mov_b32_e32 v53, v0
	v_mov_b32_e32 v54, v0
	v_mov_b32_e32 v55, v0
	v_mov_b32_e32 v8, v0
	v_mov_b32_e32 v9, v0
	v_mov_b32_e32 v10, v0
	v_mov_b32_e32 v11, v0
	v_mov_b32_e32 v12, v0
	v_mov_b32_e32 v13, v0
	v_mov_b32_e32 v14, v0
	v_mov_b32_e32 v15, v0
	v_mov_b32_e32 v24, v0
	v_mov_b32_e32 v25, v0
	v_mov_b32_e32 v26, v0
	v_mov_b32_e32 v27, v0
	v_mov_b32_e32 v28, v0
	v_mov_b32_e32 v29, v0
	v_mov_b32_e32 v30, v0
	v_mov_b32_e32 v31, v0
	v_mov_b32_e32 v40, v0
	v_mov_b32_e32 v41, v0
	v_mov_b32_e32 v42, v0
	v_mov_b32_e32 v43, v0
	v_mov_b32_e32 v44, v0
	v_mov_b32_e32 v45, v0
	v_mov_b32_e32 v46, v0
	v_mov_b32_e32 v47, v0
	v_mov_b32_e32 v56, v0
	v_mov_b32_e32 v57, v0
	v_mov_b32_e32 v58, v0
	v_mov_b32_e32 v59, v0
	v_mov_b32_e32 v60, v0
	v_mov_b32_e32 v61, v0
	v_mov_b32_e32 v62, v0
	v_mov_b32_e32 v63, v0
	v_mov_b32_e32 v64, v0
	v_mov_b32_e32 v65, v0
	v_mov_b32_e32 v66, v0
	v_mov_b32_e32 v67, v0
	v_mov_b32_e32 v68, v0
	v_mov_b32_e32 v69, v0
	v_mov_b32_e32 v70, v0
	v_mov_b32_e32 v71, v0
	v_mov_b32_e32 v80, v0
	v_mov_b32_e32 v81, v0
	v_mov_b32_e32 v82, v0
	v_mov_b32_e32 v83, v0
	v_mov_b32_e32 v84, v0
	v_mov_b32_e32 v85, v0
	v_mov_b32_e32 v86, v0
	v_mov_b32_e32 v87, v0
	v_mov_b32_e32 v96, v0
	v_mov_b32_e32 v97, v0
	v_mov_b32_e32 v98, v0
	v_mov_b32_e32 v99, v0
	v_mov_b32_e32 v100, v0
	v_mov_b32_e32 v101, v0
	v_mov_b32_e32 v102, v0
	v_mov_b32_e32 v103, v0
	v_mov_b32_e32 v112, v0
	v_mov_b32_e32 v113, v0
	v_mov_b32_e32 v114, v0
	v_mov_b32_e32 v115, v0
	v_mov_b32_e32 v116, v0
	v_mov_b32_e32 v117, v0
	v_mov_b32_e32 v118, v0
	v_mov_b32_e32 v119, v0
	v_mov_b32_e32 v72, v0
	v_mov_b32_e32 v73, v0
	v_mov_b32_e32 v74, v0
	v_mov_b32_e32 v75, v0
	v_mov_b32_e32 v76, v0
	v_mov_b32_e32 v77, v0
	v_mov_b32_e32 v78, v0
	v_mov_b32_e32 v79, v0
	v_mov_b32_e32 v88, v0
	v_mov_b32_e32 v89, v0
	v_mov_b32_e32 v90, v0
	v_mov_b32_e32 v91, v0
	v_mov_b32_e32 v92, v0
	v_mov_b32_e32 v93, v0
	v_mov_b32_e32 v94, v0
	v_mov_b32_e32 v95, v0
	v_mov_b32_e32 v104, v0
	v_mov_b32_e32 v105, v0
	v_mov_b32_e32 v106, v0
	v_mov_b32_e32 v107, v0
	v_mov_b32_e32 v108, v0
	v_mov_b32_e32 v109, v0
	v_mov_b32_e32 v110, v0
	v_mov_b32_e32 v111, v0
	v_mov_b32_e32 v120, v0
	v_mov_b32_e32 v121, v0
	v_mov_b32_e32 v122, v0
	v_mov_b32_e32 v123, v0
	v_mov_b32_e32 v124, v0
	v_mov_b32_e32 v125, v0
	v_mov_b32_e32 v126, v0
	v_mov_b32_e32 v127, v0
	.p2alignl 6, 3212836864

.LBB0_2211:
	s_ashr_i32 s19, s18, 31
	s_lshl_b64 s[20:21], s[18:19], 20
	s_add_u32 s20, s2, s20
	s_addc_u32 s21, s3, s21
	s_and_b64 s[22:23], s[8:9], exec
	s_cselect_b32 s19, s21, s29
	s_cselect_b32 s25, s20, s28
	s_ashr_i32 s17, s16, 31
	s_lshl_b64 s[22:23], s[16:17], 20
	s_add_u32 s22, s0, s22
	s_addc_u32 s23, s1, s23
	s_and_b64 s[34:35], s[8:9], exec
	s_cselect_b32 s17, s23, s31
	s_cselect_b32 s49, s22, s30
	s_add_u32 s50, s30, 0x100
	v_mov_b32_e32 v0, 0
	s_mov_b32 s56, s52
	s_addc_u32 s51, s31, 0
	s_mov_b32 s52, -2
	s_waitcnt lgkmcnt(0)
	v_mov_b32_e32 v1, v0
	v_mov_b32_e32 v2, v0
	v_mov_b32_e32 v3, v0
	v_mov_b32_e32 v4, v0
	v_mov_b32_e32 v5, v0
	v_mov_b32_e32 v6, v0
	v_mov_b32_e32 v7, v0
	v_mov_b32_e32 v16, v0
	v_mov_b32_e32 v17, v0
	v_mov_b32_e32 v18, v0
	v_mov_b32_e32 v19, v0
	v_mov_b32_e32 v20, v0
	v_mov_b32_e32 v21, v0
	v_mov_b32_e32 v22, v0
	v_mov_b32_e32 v23, v0
	v_mov_b32_e32 v32, v0
	v_mov_b32_e32 v33, v0
	v_mov_b32_e32 v34, v0
	v_mov_b32_e32 v35, v0
	v_mov_b32_e32 v36, v0
	v_mov_b32_e32 v37, v0
	v_mov_b32_e32 v38, v0
	v_mov_b32_e32 v39, v0
	v_mov_b32_e32 v48, v0
	v_mov_b32_e32 v49, v0
	v_mov_b32_e32 v50, v0
	v_mov_b32_e32 v51, v0
	v_mov_b32_e32 v52, v0
	v_mov_b32_e32 v53, v0
	v_mov_b32_e32 v54, v0
	v_mov_b32_e32 v55, v0
	v_mov_b32_e32 v8, v0
	v_mov_b32_e32 v9, v0
	v_mov_b32_e32 v10, v0
	v_mov_b32_e32 v11, v0
	v_mov_b32_e32 v12, v0
	v_mov_b32_e32 v13, v0
	v_mov_b32_e32 v14, v0
	v_mov_b32_e32 v15, v0
	v_mov_b32_e32 v24, v0
	v_mov_b32_e32 v25, v0
	v_mov_b32_e32 v26, v0
	v_mov_b32_e32 v27, v0
	v_mov_b32_e32 v28, v0
	v_mov_b32_e32 v29, v0
	v_mov_b32_e32 v30, v0
	v_mov_b32_e32 v31, v0
	v_mov_b32_e32 v40, v0
	v_mov_b32_e32 v41, v0
	v_mov_b32_e32 v42, v0
	v_mov_b32_e32 v43, v0
	v_mov_b32_e32 v44, v0
	v_mov_b32_e32 v45, v0
	v_mov_b32_e32 v46, v0
	v_mov_b32_e32 v47, v0
	v_mov_b32_e32 v56, v0
	v_mov_b32_e32 v57, v0
	v_mov_b32_e32 v58, v0
	v_mov_b32_e32 v59, v0
	v_mov_b32_e32 v60, v0
	v_mov_b32_e32 v61, v0
	v_mov_b32_e32 v62, v0
	v_mov_b32_e32 v63, v0
	v_mov_b32_e32 v64, v0
	v_mov_b32_e32 v65, v0
	v_mov_b32_e32 v66, v0
	v_mov_b32_e32 v67, v0
	v_mov_b32_e32 v68, v0
	v_mov_b32_e32 v69, v0
	v_mov_b32_e32 v70, v0
	v_mov_b32_e32 v71, v0
	v_mov_b32_e32 v80, v0
	v_mov_b32_e32 v81, v0
	v_mov_b32_e32 v82, v0
	v_mov_b32_e32 v83, v0
	v_mov_b32_e32 v84, v0
	v_mov_b32_e32 v85, v0
	v_mov_b32_e32 v86, v0
	v_mov_b32_e32 v87, v0
	v_mov_b32_e32 v96, v0
	v_mov_b32_e32 v97, v0
	v_mov_b32_e32 v98, v0
	v_mov_b32_e32 v99, v0
	v_mov_b32_e32 v100, v0
	v_mov_b32_e32 v101, v0
	v_mov_b32_e32 v102, v0
	v_mov_b32_e32 v103, v0
	v_mov_b32_e32 v112, v0
	v_mov_b32_e32 v113, v0
	v_mov_b32_e32 v114, v0
	v_mov_b32_e32 v115, v0
	v_mov_b32_e32 v116, v0
	v_mov_b32_e32 v117, v0
	v_mov_b32_e32 v118, v0
	v_mov_b32_e32 v119, v0
	v_mov_b32_e32 v72, v0
	v_mov_b32_e32 v73, v0
	v_mov_b32_e32 v74, v0
	v_mov_b32_e32 v75, v0
	v_mov_b32_e32 v76, v0
	v_mov_b32_e32 v77, v0
	v_mov_b32_e32 v78, v0
	v_mov_b32_e32 v79, v0
	v_mov_b32_e32 v88, v0
	v_mov_b32_e32 v89, v0
	v_mov_b32_e32 v90, v0
	v_mov_b32_e32 v91, v0
	v_mov_b32_e32 v92, v0
	v_mov_b32_e32 v93, v0
	v_mov_b32_e32 v94, v0
	v_mov_b32_e32 v95, v0
	v_mov_b32_e32 v104, v0
	v_mov_b32_e32 v105, v0
	v_mov_b32_e32 v106, v0
	v_mov_b32_e32 v107, v0
	v_mov_b32_e32 v108, v0
	v_mov_b32_e32 v109, v0
	v_mov_b32_e32 v110, v0
	v_mov_b32_e32 v111, v0
	v_mov_b32_e32 v120, v0
	v_mov_b32_e32 v121, v0
	v_mov_b32_e32 v122, v0
	v_mov_b32_e32 v123, v0
	v_mov_b32_e32 v124, v0
	v_mov_b32_e32 v125, v0
	v_mov_b32_e32 v126, v0
	v_mov_b32_e32 v127, v0
	.p2alignl 6, 3212836864

.LBB0_2310:
	s_ashr_i32 s15, s14, 31
	s_lshl_b64 s[16:17], s[14:15], 20
	v_readlane_b32 s18, v234, 22
	v_readlane_b32 s19, v234, 23
	s_add_u32 s16, s18, s16
	s_addc_u32 s17, s19, s17
	s_and_b64 s[18:19], s[6:7], exec
	s_cselect_b32 s15, s17, s21
	s_cselect_b32 s44, s16, s20
	s_ashr_i32 s13, s12, 31
	s_lshl_b64 s[18:19], s[12:13], 20
	s_add_u32 s18, s27, s18
	s_addc_u32 s19, s28, s19
	s_and_b64 s[24:25], s[6:7], exec
	s_cselect_b32 s13, s19, s23
	s_cselect_b32 s45, s18, s22
	s_add_u32 s20, s20, 0x80080
	s_addc_u32 s21, s21, 0
	s_add_u32 s46, s22, 0x100
	v_mov_b32_e32 v8, 0
	s_addc_u32 s47, s23, 0
	s_mov_b32 s48, -2
	v_mov_b32_e32 v9, v8
	v_mov_b32_e32 v10, v8
	v_mov_b32_e32 v11, v8
	v_mov_b32_e32 v12, v8
	v_mov_b32_e32 v13, v8
	v_mov_b32_e32 v14, v8
	v_mov_b32_e32 v15, v8
	v_mov_b32_e32 v24, v8
	v_mov_b32_e32 v25, v8
	v_mov_b32_e32 v26, v8
	v_mov_b32_e32 v27, v8
	v_mov_b32_e32 v28, v8
	v_mov_b32_e32 v29, v8
	v_mov_b32_e32 v30, v8
	v_mov_b32_e32 v31, v8
	v_mov_b32_e32 v40, v8
	v_mov_b32_e32 v41, v8
	v_mov_b32_e32 v42, v8
	v_mov_b32_e32 v43, v8
	v_mov_b32_e32 v44, v8
	v_mov_b32_e32 v45, v8
	v_mov_b32_e32 v46, v8
	v_mov_b32_e32 v47, v8
	v_mov_b32_e32 v56, v8
	v_mov_b32_e32 v57, v8
	v_mov_b32_e32 v58, v8
	v_mov_b32_e32 v59, v8
	v_mov_b32_e32 v60, v8
	v_mov_b32_e32 v61, v8
	v_mov_b32_e32 v62, v8
	v_mov_b32_e32 v63, v8
	v_mov_b32_e32 v0, v8
	v_mov_b32_e32 v1, v8
	v_mov_b32_e32 v2, v8
	v_mov_b32_e32 v3, v8
	v_mov_b32_e32 v4, v8
	v_mov_b32_e32 v5, v8
	v_mov_b32_e32 v6, v8
	v_mov_b32_e32 v7, v8
	v_mov_b32_e32 v16, v8
	v_mov_b32_e32 v17, v8
	v_mov_b32_e32 v18, v8
	v_mov_b32_e32 v19, v8
	v_mov_b32_e32 v20, v8
	v_mov_b32_e32 v21, v8
	v_mov_b32_e32 v22, v8
	v_mov_b32_e32 v23, v8
	v_mov_b32_e32 v32, v8
	v_mov_b32_e32 v33, v8
	v_mov_b32_e32 v34, v8
	v_mov_b32_e32 v35, v8
	v_mov_b32_e32 v36, v8
	v_mov_b32_e32 v37, v8
	v_mov_b32_e32 v38, v8
	v_mov_b32_e32 v39, v8
	v_mov_b32_e32 v48, v8
	v_mov_b32_e32 v49, v8
	v_mov_b32_e32 v50, v8
	v_mov_b32_e32 v51, v8
	v_mov_b32_e32 v52, v8
	v_mov_b32_e32 v53, v8
	v_mov_b32_e32 v54, v8
	v_mov_b32_e32 v55, v8
	v_mov_b32_e32 v68, v8
	v_mov_b32_e32 v69, v8
	v_mov_b32_e32 v70, v8
	v_mov_b32_e32 v71, v8
	v_mov_b32_e32 v76, v8
	v_mov_b32_e32 v77, v8
	v_mov_b32_e32 v78, v8
	v_mov_b32_e32 v79, v8
	v_mov_b32_e32 v88, v8
	v_mov_b32_e32 v89, v8
	v_mov_b32_e32 v90, v8
	v_mov_b32_e32 v91, v8
	v_mov_b32_e32 v92, v8
	v_mov_b32_e32 v93, v8
	v_mov_b32_e32 v94, v8
	v_mov_b32_e32 v95, v8
	v_mov_b32_e32 v104, v8
	v_mov_b32_e32 v105, v8
	v_mov_b32_e32 v106, v8
	v_mov_b32_e32 v107, v8
	v_mov_b32_e32 v108, v8
	v_mov_b32_e32 v109, v8
	v_mov_b32_e32 v110, v8
	v_mov_b32_e32 v111, v8
	v_mov_b32_e32 v120, v8
	v_mov_b32_e32 v121, v8
	v_mov_b32_e32 v122, v8
	v_mov_b32_e32 v123, v8
	v_mov_b32_e32 v124, v8
	v_mov_b32_e32 v125, v8
	v_mov_b32_e32 v126, v8
	v_mov_b32_e32 v127, v8
	v_mov_b32_e32 v64, v8
	v_mov_b32_e32 v65, v8
	v_mov_b32_e32 v66, v8
	v_mov_b32_e32 v67, v8
	v_mov_b32_e32 v72, v8
	v_mov_b32_e32 v73, v8
	v_mov_b32_e32 v74, v8
	v_mov_b32_e32 v75, v8
	v_mov_b32_e32 v80, v8
	v_mov_b32_e32 v81, v8
	v_mov_b32_e32 v82, v8
	v_mov_b32_e32 v83, v8
	v_mov_b32_e32 v84, v8
	v_mov_b32_e32 v85, v8
	v_mov_b32_e32 v86, v8
	v_mov_b32_e32 v87, v8
	v_mov_b32_e32 v96, v8
	v_mov_b32_e32 v97, v8
	v_mov_b32_e32 v98, v8
	v_mov_b32_e32 v99, v8
	v_mov_b32_e32 v100, v8
	v_mov_b32_e32 v101, v8
	v_mov_b32_e32 v102, v8
	v_mov_b32_e32 v103, v8
	v_mov_b32_e32 v112, v8
	v_mov_b32_e32 v113, v8
	v_mov_b32_e32 v114, v8
	v_mov_b32_e32 v115, v8
	v_mov_b32_e32 v116, v8
	v_mov_b32_e32 v117, v8
	v_mov_b32_e32 v118, v8
	v_mov_b32_e32 v119, v8
	.p2alignl 6, 3212836864

.LBB0_2392:
	s_add_u32 s44, s20, 0x100
	v_mov_b32_e32 v0, 0
	s_addc_u32 s45, s21, 0
	s_mov_b32 s46, -2
	s_waitcnt lgkmcnt(0)
	v_mov_b32_e32 v1, v0
	v_mov_b32_e32 v2, v0
	v_mov_b32_e32 v3, v0
	v_mov_b32_e32 v4, v0
	v_mov_b32_e32 v5, v0
	v_mov_b32_e32 v6, v0
	v_mov_b32_e32 v7, v0
	v_mov_b32_e32 v16, v0
	v_mov_b32_e32 v17, v0
	v_mov_b32_e32 v18, v0
	v_mov_b32_e32 v19, v0
	v_mov_b32_e32 v20, v0
	v_mov_b32_e32 v21, v0
	v_mov_b32_e32 v22, v0
	v_mov_b32_e32 v23, v0
	v_mov_b32_e32 v32, v0
	v_mov_b32_e32 v33, v0
	v_mov_b32_e32 v34, v0
	v_mov_b32_e32 v35, v0
	v_mov_b32_e32 v36, v0
	v_mov_b32_e32 v37, v0
	v_mov_b32_e32 v38, v0
	v_mov_b32_e32 v39, v0
	v_mov_b32_e32 v48, v0
	v_mov_b32_e32 v49, v0
	v_mov_b32_e32 v50, v0
	v_mov_b32_e32 v51, v0
	v_mov_b32_e32 v52, v0
	v_mov_b32_e32 v53, v0
	v_mov_b32_e32 v54, v0
	v_mov_b32_e32 v55, v0
	v_mov_b32_e32 v8, v0
	v_mov_b32_e32 v9, v0
	v_mov_b32_e32 v10, v0
	v_mov_b32_e32 v11, v0
	v_mov_b32_e32 v12, v0
	v_mov_b32_e32 v13, v0
	v_mov_b32_e32 v14, v0
	v_mov_b32_e32 v15, v0
	v_mov_b32_e32 v24, v0
	v_mov_b32_e32 v25, v0
	v_mov_b32_e32 v26, v0
	v_mov_b32_e32 v27, v0
	v_mov_b32_e32 v28, v0
	v_mov_b32_e32 v29, v0
	v_mov_b32_e32 v30, v0
	v_mov_b32_e32 v31, v0
	v_mov_b32_e32 v40, v0
	v_mov_b32_e32 v41, v0
	v_mov_b32_e32 v42, v0
	v_mov_b32_e32 v43, v0
	v_mov_b32_e32 v44, v0
	v_mov_b32_e32 v45, v0
	v_mov_b32_e32 v46, v0
	v_mov_b32_e32 v47, v0
	v_mov_b32_e32 v56, v0
	v_mov_b32_e32 v57, v0
	v_mov_b32_e32 v58, v0
	v_mov_b32_e32 v59, v0
	v_mov_b32_e32 v60, v0
	v_mov_b32_e32 v61, v0
	v_mov_b32_e32 v62, v0
	v_mov_b32_e32 v63, v0
	v_mov_b32_e32 v64, v0
	v_mov_b32_e32 v65, v0
	v_mov_b32_e32 v66, v0
	v_mov_b32_e32 v67, v0
	v_mov_b32_e32 v68, v0
	v_mov_b32_e32 v69, v0
	v_mov_b32_e32 v70, v0
	v_mov_b32_e32 v71, v0
	v_mov_b32_e32 v80, v0
	v_mov_b32_e32 v81, v0
	v_mov_b32_e32 v82, v0
	v_mov_b32_e32 v83, v0
	v_mov_b32_e32 v84, v0
	v_mov_b32_e32 v85, v0
	v_mov_b32_e32 v86, v0
	v_mov_b32_e32 v87, v0
	v_mov_b32_e32 v96, v0
	v_mov_b32_e32 v97, v0
	v_mov_b32_e32 v98, v0
	v_mov_b32_e32 v99, v0
	v_mov_b32_e32 v100, v0
	v_mov_b32_e32 v101, v0
	v_mov_b32_e32 v102, v0
	v_mov_b32_e32 v103, v0
	v_mov_b32_e32 v112, v0
	v_mov_b32_e32 v113, v0
	v_mov_b32_e32 v114, v0
	v_mov_b32_e32 v115, v0
	v_mov_b32_e32 v116, v0
	v_mov_b32_e32 v117, v0
	v_mov_b32_e32 v118, v0
	v_mov_b32_e32 v119, v0
	v_mov_b32_e32 v72, v0
	v_mov_b32_e32 v73, v0
	v_mov_b32_e32 v74, v0
	v_mov_b32_e32 v75, v0
	v_mov_b32_e32 v76, v0
	v_mov_b32_e32 v77, v0
	v_mov_b32_e32 v78, v0
	v_mov_b32_e32 v79, v0
	v_mov_b32_e32 v88, v0
	v_mov_b32_e32 v89, v0
	v_mov_b32_e32 v90, v0
	v_mov_b32_e32 v91, v0
	v_mov_b32_e32 v92, v0
	v_mov_b32_e32 v93, v0
	v_mov_b32_e32 v94, v0
	v_mov_b32_e32 v95, v0
	v_mov_b32_e32 v104, v0
	v_mov_b32_e32 v105, v0
	v_mov_b32_e32 v106, v0
	v_mov_b32_e32 v107, v0
	v_mov_b32_e32 v108, v0
	v_mov_b32_e32 v109, v0
	v_mov_b32_e32 v110, v0
	v_mov_b32_e32 v111, v0
	v_mov_b32_e32 v120, v0
	v_mov_b32_e32 v121, v0
	v_mov_b32_e32 v122, v0
	v_mov_b32_e32 v123, v0
	v_mov_b32_e32 v124, v0
	v_mov_b32_e32 v125, v0
	v_mov_b32_e32 v126, v0
	v_mov_b32_e32 v127, v0
	.p2alignl 6, 3212836864
